# static LDS grown to 160KiB; SEL attention loop stages 8 K/V tile slots and synchronises once per FOUR key tiles
# speedup vs baseline: 1.0042x; 1.0042x over previous
; DI float bflo(unsigned w) { return __uint_as_float(w << 16); }
; DI float bfhi(unsigned w) { return __uint_as_float(w & 0xffff0000u); }
; #define GATES WSP(float, WS_GATES)
; #define MASKS WSP(unsigned, WS_MASK)
; #define lds fresh_lds(lds0)
; template <int DQK, int MODE> ...
;     ...
;     FL_GLOAD(t0);
;     __syncthreads();
;     FL_LSTORE(0);
;     if (t0 + 1 < t1) FL_GLOAD(t0 + 1);
;     __syncthreads();
; __global__ void __launch_bounds__(512) mega_fwd(Params P) {
;     ...
;                 const int qb = 31 - it / 24, r24 = it % 24, bh = r24 % 12, b = bh / 6, h = bh % 6, g = h / 3, q0 = qb * 256;
;                 const size_t rb = (size_t)b * SEQ; const size_t qrow = rb + q0 + 32 * wid + r32;
;                 if (r24 < 12) {
;                     f32x16 tot[2]; tot[0] = (f32x16){}; tot[1] = (f32x16){};
;                     flash_unit<96, MODE_CAUSAL>(lds, wv0, QMLA + (rb + q0) * 576 + h * 96, 576, KVB + rb * 768 + h * 64, 768, PROJ + rb * NPROJ + PC_KR, NPROJ,
;                                                 KVB + rb * 768 + 384 + h * 64, 768, q0, 0, (q0 + 256) / 64, 0.10206207261596577f * LOG2E, (u32x4){}, 1.f, tot, nullptr, WSP(float, WS_ROPE));
;                     store_o(tot, HN + qrow * DM + h * 64, hi);
;                 } else {
;                     const float g1 = GATES[qrow * 32 + h * 3 + 1], g2 = GATES[qrow * 32 + h * 3 + 2];
;                     const u32x4 mw = *(const u32x4*)(MASKS + ((size_t)(b * 2 + g) * SEQ + q0 + 32 * wid + r32) * 4);
;                     f32x16 tot[2];
;                     { const bf16_t* oc = OCMP + qrow * 384 + h * 64;
; #pragma unroll
;                       for (int d0 = 0; d0 < 2; ++d0)
; #pragma unroll
;                           for (int j = 0; j < 4; ++j) { const u32x2 w = *(const u32x2*)(oc + 32 * d0 + 8 * j + 4 * hi); tot[d0][4 * j] = bflo(w.x); tot[d0][4 * j + 1] = bfhi(w.x); tot[d0][4 * j + 2] = bflo(w.y); tot[d0][4 * j + 3] = bfhi(w.y); } }
;                     const bf16_t* Qp = PROJ + (rb + q0) * NPROJ + PC_NQ + 64 * h;
;                     flash_unit<64, MODE_SEL>(lds, wv0, Qp, NPROJ, PROJ + rb * NPROJ + PC_KS + 64 * g, NPROJ, nullptr, 0, PROJ + rb * NPROJ + PC_VS + 64 * g, NPROJ,
;                                              q0, 0, (q0 + 256) / 64, 0.125f * LOG2E, mw, g1, tot, nullptr);
.LBB0_1306:
	s_or_b64 exec, exec, s[0:1]
	v_mov_b32_e32 v0, s38
	s_waitcnt lgkmcnt(0)
	s_barrier
	ds_read_b32 v0, v0
	s_movk_i32 s0, 0x3ff
	s_waitcnt lgkmcnt(0)
	v_cmp_lt_i32_e32 vcc, s0, v0
	v_readfirstlane_b32 s34, v0
	s_mov_b64 s[0:1], -1
	s_cbranch_vccnz .LBB0_1303
	s_cmpk_lt_i32 s34, 0x300
	s_cbranch_scc0 .LBB0_1372
	s_mul_hi_i32 s0, s34, 0xd5555555
	s_lshr_b32 s1, s0, 31
	s_lshr_b32 s0, s0, 2
	s_add_i32 s4, s0, s1
	s_mul_hi_i32 s0, s34, 0x2aaaaaab
	s_lshr_b32 s1, s0, 31
	s_lshr_b32 s0, s0, 2
	s_add_i32 s0, s0, s1
	s_mul_i32 s0, s0, 24
	s_sub_i32 s6, s34, s0
	s_mul_i32 s0, s6, 43
	s_sext_i32_i16 s1, s0
	s_lshr_b32 s1, s1, 9
	s_bfe_u32 s0, s0, 0x1000f
	s_add_i32 s0, s1, s0
	s_mul_i32 s0, s0, 12
	s_sub_i32 s1, s6, s0
	s_bfe_i32 s0, s1, 0x80000
	s_mul_i32 s0, s0, 43
	s_bfe_u32 s5, s0, 0x1000f
	s_bfe_u32 s0, s0, 0x80008
	s_add_i32 s0, s0, s5
	s_mul_i32 s5, s0, 6
	s_sub_i32 s1, s1, s5
	s_lshl_b32 s35, s4, 8
	s_bfe_i64 s[8:9], s[0:1], 0x80000
	s_add_i32 s36, s35, 0x1f00
	s_lshl_b64 s[4:5], s[8:9], 13
	s_add_u32 s26, s4, s36
	s_addc_u32 s27, s5, 0
	s_sext_i32_i8 s37, s1
	v_lshl_add_u64 v[180:181], s[26:27], 0, v[174:175]
	s_mov_b64 s[4:5], -1
	s_cmp_gt_i32 s6, 11
	s_mul_hi_i32 s45, s8, 0x2800000
	s_mul_i32 s46, s8, 0x2800000
	s_cbranch_scc0 .LBB0_1346
	s_bfe_i32 s1, s1, 0x80000
	s_mulk_i32 s1, 0x56
	s_bfe_u32 s4, s1, 0x1000f
	s_bfe_u32 s1, s1, 0x80008
	s_add_i32 s1, s1, s4
	s_sext_i32_i8 s6, s1
	s_sext_i32_i8 s0, s0
	s_lshl_b32 s0, s0, 14
	s_lshl_b32 s1, s6, 13
	s_add_i32 s1, s1, s0
	s_add_u32 s0, s1, s36
	s_addc_u32 s1, 0, 0
	v_mov_b64_e32 v[6:7], s[18:19]
	v_lshl_add_u64 v[4:5], s[0:1], 0, v[174:175]
	v_mad_u64_u32 v[6:7], s[0:1], v180, s72, v[6:7]
	v_mov_b32_e32 v0, v7
	v_lshlrev_b64 v[2:3], 7, v[180:181]
	v_mad_u64_u32 v[8:9], s[0:1], v181, s72, v[0:1]
	s_mul_i32 s80, s37, 3
	v_lshl_add_u64 v[2:3], s[14:15], 0, v[2:3]
	s_mul_i32 s0, s27, 0x1400
	s_mul_hi_u32 s1, s26, 0x1400
	v_lshl_add_u64 v[2:3], s[80:81], 2, v[2:3]
	s_lshl_b32 s9, s37, 6
	s_lshl_b32 s80, s37, 7
	s_add_i32 s1, s1, s0
	s_mul_i32 s0, s26, 0x1400
	s_add_u32 s0, s39, s0
	v_mov_b32_e32 v7, v8
	s_addc_u32 s1, s40, s1
	v_lshl_add_u64 v[6:7], v[6:7], 0, s[80:81]
	v_mov_b32_e32 v179, v1
	s_add_u32 s30, s0, s80
	v_lshl_add_u64 v[4:5], v[4:5], 4, s[16:17]
	v_lshl_add_u64 v[6:7], v[6:7], 0, v[178:179]
	s_addc_u32 s31, s1, 0
	s_mov_b32 s1, s81
	v_mov_b32_e32 v0, v1
	flat_load_dwordx2 v[182:183], v[2:3] offset:4
	s_nop 0
	flat_load_dwordx4 v[2:5], v[4:5]
	s_nop 0
	flat_load_dwordx2 v[198:199], v[6:7]
	flat_load_dwordx2 v[196:197], v[6:7] offset:16
	flat_load_dwordx2 v[194:195], v[6:7] offset:32
	flat_load_dwordx2 v[192:193], v[6:7] offset:48
	flat_load_dwordx2 v[190:191], v[6:7] offset:64
	flat_load_dwordx2 v[188:189], v[6:7] offset:80
	flat_load_dwordx2 v[186:187], v[6:7] offset:96
	flat_load_dwordx2 v[184:185], v[6:7] offset:112
	v_readlane_b32 s7, v254, 6
	v_mbcnt_lo_u32_b32 v0, -1, v0
	v_mbcnt_hi_u32_b32 v26, -1, v0
	v_and_b32_e32 v27, 31, v26
	v_bfe_u32 v28, v26, 5, 1
	v_or_b32_e32 v0, s7, v27
	v_mov_b64_e32 v[6:7], s[30:31]
	v_mad_i64_i32 v[6:7], s[4:5], v0, s69, v[6:7]
	v_lshlrev_b32_e32 v0, 4, v28
	v_lshl_add_u64 v[6:7], v[6:7], 0, v[0:1]
	s_waitcnt vmcnt(0)
	flat_load_dwordx4 v[84:87], v[6:7] offset:832
	flat_load_dwordx4 v[80:83], v[6:7] offset:864
	flat_load_dwordx4 v[10:13], v[6:7] offset:896
	s_nop 0
	flat_load_dwordx4 v[6:9], v[6:7] offset:928
	s_add_u32 s0, s39, s46
	v_or_b32_e32 v14, s79, v26
	s_addc_u32 s4, s40, s45
	s_lshl_b32 s5, s6, 7
	v_and_b32_e32 v15, 7, v26
	v_ashrrev_i32_e32 v24, 3, v14
	s_add_u32 s28, s0, s5
	v_lshlrev_b32_e32 v29, 4, v15
	v_mul_lo_u32 v14, v24, s69
	v_mov_b32_e32 v23, v1
	s_addc_u32 s29, s4, 0
	v_or_b32_e32 v22, v29, v14
	v_lshl_add_u64 v[18:19], s[28:29], 0, v[22:23]
	s_movk_i32 s4, 0x90
	v_mul_lo_u32 v23, v24, s4
	v_mov_b32_e32 v25, v1
	v_add3_u32 v129, s1, v23, v29
	v_add_u32_e32 v24, 0x50000, v22
	v_lshl_add_u64 v[24:25], s[28:29], 0, v[24:25]
	v_add_u32_e32 v226, 0xa0000, v22
	v_mov_b32_e32 v227, v1
	v_lshl_add_u64 v[226:227], s[28:29], 0, v[226:227]
	v_add_u32_e32 v232, 0xf0000, v22
	v_mov_b32_e32 v233, v1
	v_lshl_add_u64 v[232:233], s[28:29], 0, v[232:233]
	v_mad_u32_u24 v131, v27, s4, v0
	v_lshlrev_b32_e32 v128, 2, v28
	v_lshrrev_b32_e32 v0, 2, v26
	s_add_i32 s0, s35, 0x2000
	s_add_i32 s48, s36, s7
	v_and_or_b32 v0, v0, 3, v128
	v_mov_b32_e32 v30, v1
	v_mov_b32_e32 v31, v1
	s_lshr_b32 s47, s0, 6
	v_mov_b32_e32 v23, v1
	v_mov_b32_e32 v28, v1
	v_mov_b32_e32 v29, v1
	s_mov_b32 s53, s81
	s_mov_b32 s50, 0
	s_or_b32 s49, s48, 31
	s_add_i32 s0, s47, -1
	v_mov_b32_e32 v179, 0
	s_mov_b32 s51, 63
	global_load_dwordx4 v[14:17], v[18:19], off offset:2112
	s_nop 0
	global_load_dwordx4 v[18:21], v[18:19], off offset:2368
	global_load_dwordx4 v[88:91], v[24:25], off offset:2368
	global_load_dwordx4 v[92:95], v[24:25], off offset:2112
	global_load_dwordx4 v[222:225], v[226:227], off offset:2368
	global_load_dwordx4 v[218:221], v[226:227], off offset:2112
	global_load_dwordx4 v[238:241], v[232:233], off offset:2368
	global_load_dwordx4 v[234:237], v[232:233], off offset:2112
	s_waitcnt vmcnt(0) lgkmcnt(0)
	s_waitcnt lgkmcnt(0)
	s_barrier
	s_waitcnt vmcnt(0)
	v_add_u32_e32 v230, 0x12000, v129
	ds_write_b128 v129, v[14:17]
	ds_write_b128 v230, v[18:21]
	v_add_u32_e32 v229, 0x2400, v129
	v_add_u32_e32 v230, 0x2400, v230
	ds_write_b128 v229, v[92:95]
	ds_write_b128 v230, v[88:91]
	v_add_u32_e32 v229, 0x2400, v229
	v_add_u32_e32 v230, 0x2400, v230
	ds_write_b128 v229, v[218:221]
	ds_write_b128 v230, v[222:225]
	v_add_u32_e32 v229, 0x2400, v229
	v_add_u32_e32 v230, 0x2400, v230
	ds_write_b128 v229, v[234:237]
	ds_write_b128 v230, v[238:241]
	s_cmp_lt_u32 s47, 5
	s_cbranch_scc1 .Lselq_pro_done
	v_add_u32_e32 v228, 0x140000, v22
	v_mov_b32_e32 v229, v1
	v_lshl_add_u64 v[228:229], s[28:29], 0, v[228:229]
	global_load_dwordx4 v[92:95], v[228:229], off offset:2112
	global_load_dwordx4 v[88:91], v[228:229], off offset:2368
	v_add_u32_e32 v230, 0x190000, v22
	v_mov_b32_e32 v231, v1
	v_lshl_add_u64 v[230:231], s[28:29], 0, v[230:231]
	global_load_dwordx4 v[218:221], v[230:231], off offset:2112
	global_load_dwordx4 v[222:225], v[230:231], off offset:2368
.Lselq_pro_done:
	v_lshlrev_b32_e32 v14, 1, v26
	v_and_b32_e32 v14, 32, v14
	v_lshlrev_b32_e32 v16, 3, v26
	v_and_or_b32 v14, v16, 24, v14
	v_or_b32_e32 v15, s48, v27
	v_mad_u32_u24 v130, v0, s4, v14
	v_add_u32_e32 v0, 0x190000, v22
	v_mov_b32_e32 v16, v1
	v_mov_b32_e32 v17, v1
	v_mov_b32_e32 v18, v1
	v_mov_b32_e32 v19, v1
	v_mov_b32_e32 v20, v1
	v_mov_b32_e32 v21, v1
	v_mov_b32_e32 v22, v1
	v_mov_b32_e32 v24, v1
	v_mov_b32_e32 v25, v1
	v_mov_b32_e32 v26, v1
	v_mov_b32_e32 v27, v1
	v_mov_b64_e32 v[46:47], v[30:31]
	v_mov_b32_e32 v14, 0xf149f2ca
	v_mov_b64_e32 v[44:45], v[28:29]
	v_mov_b64_e32 v[42:43], v[26:27]
	v_mov_b64_e32 v[40:41], v[24:25]
	v_mov_b64_e32 v[38:39], v[22:23]
	v_mov_b64_e32 v[36:37], v[20:21]
	v_mov_b64_e32 v[34:35], v[18:19]
	v_mov_b64_e32 v[32:33], v[16:17]
	s_waitcnt lgkmcnt(0)
	s_barrier
	s_branch .LBB0_1311

; template <int DQK, int MODE> ...
;     ...
;         if (active) {
;             f32x16 s[2];
;             bf16x8 ka[2][NKS]; s16x4 vlo[2][2][2], vhi[2][2][2];
;             {
;                 const unsigned kaddr = (unsigned)(unsigned long)(lds + AT_K + cur * KBUF) + (unsigned)(r32 * KP2 + hi * 16);
;                 const unsigned vaddr = (unsigned)(unsigned long)(lds + AT_V + cur * VBUF) + (unsigned)((4 * hi + ((lane & 15) >> 2)) * VP2 + 32 * ((lane >> 4) & 1) + 8 * (lane & 3));
; #pragma unroll
;                 for (int kb = 0; kb < 2; ++kb)
; #pragma unroll
;                     for (int ks = 0; ks < NKS; ++ks) asm volatile("ds_read_b128 %0, %1 offset:%2" : "=v"(ka[kb][ks]) : "v"(kaddr), "n"(kb * 32 * KP2 + ks * 32) : "memory");
; #pragma unroll
;                 for (int s2 = 0; s2 < 2; ++s2)
; #pragma unroll
;                     for (int d0 = 0; d0 < 2; ++d0) {
;                         asm volatile("ds_read_b64_tr_b16 %0, %1 offset:%2" : "=v"(vlo[0][s2][d0]) : "v"(vaddr), "n"(16 * s2 * VP2 + 64 * d0) : "memory");
;                         asm volatile("ds_read_b64_tr_b16 %0, %1 offset:%2" : "=v"(vhi[0][s2][d0]) : "v"(vaddr), "n"(16 * s2 * VP2 + 64 * d0 + 8 * VP2) : "memory");
;                     }
;                 asm volatile("s_waitcnt lgkmcnt(8)" ::: "memory");
; #pragma unroll
;                 for (int kb = 0; kb < 2; ++kb)
; #pragma unroll
;                     for (int ks = 0; ks < NKS; ++ks) asm volatile("" : "+v"(ka[kb][ks]));
;                 s[0] = (f32x16){}; s[1] = (f32x16){};
;                 __builtin_amdgcn_s_setprio(1);
; #pragma unroll
;                 for (int ks = 0; ks < NKS; ++ks) { s[0] = MFMA32(ka[0][ks], qf[ks], s[0]); s[1] = MFMA32(ka[1][ks], qf[ks], s[1]); }
;                 __builtin_amdgcn_s_setprio(0);
; #pragma unroll
;                 for (int s2 = 0; s2 < 2; ++s2)
; #pragma unroll
;                     for (int d0 = 0; d0 < 2; ++d0) {
;                         asm volatile("ds_read_b64_tr_b16 %0, %1 offset:%2" : "=v"(vlo[1][s2][d0]) : "v"(vaddr), "n"((32 + 16 * s2) * VP2 + 64 * d0) : "memory");
;                         asm volatile("ds_read_b64_tr_b16 %0, %1 offset:%2" : "=v"(vhi[1][s2][d0]) : "v"(vaddr), "n"((32 + 16 * s2) * VP2 + 64 * d0 + 8 * VP2) : "memory");
;                     }
;             }
;             bool need_mask;
;             if (MODE == MODE_CMP) need_mask = true;
.LBB0_1311:
	s_and_b32 s52, s50, 7
	s_sub_i32 s4, s51, 63
	s_cmp_gt_i32 s4, s49
	s_cbranch_scc1 .LBB0_1319
	s_mul_i32 s4, s52, 0x2400
	s_add_i32 s4, s1, s4
	v_add_u32_e32 v52, s4, v131
	ds_read_b128 v[64:67], v52 offset:0
	ds_read_b128 v[104:107], v52 offset:32
	ds_read_b128 v[108:111], v52 offset:64
	ds_read_b128 v[132:135], v52 offset:0x60
	ds_read_b128 v[48:51], v52 offset:0x1200
	ds_read_b128 v[68:71], v52 offset:0x1220
	ds_read_b128 v[72:75], v52 offset:0x1240
	s_cmp_gt_u32 s52, 5
	s_cselect_b32 s5, 0xc00, 0
	s_add_i32 s5, s5, 0x12000
	s_add_i32 s4, s4, s5
	ds_read_b128 v[76:79], v52 offset:0x1260
	v_add_u32_e32 v136, s4, v130
	ds_read_b64_tr_b16 v[116:117], v136 offset:0
	ds_read_b64_tr_b16 v[118:119], v136 offset:0x480
	ds_read_b64_tr_b16 v[112:113], v136 offset:64
	ds_read_b64_tr_b16 v[114:115], v136 offset:0x4c0
	ds_read_b64_tr_b16 v[100:101], v136 offset:0x900
	ds_read_b64_tr_b16 v[102:103], v136 offset:0xd80
	ds_read_b64_tr_b16 v[96:97], v136 offset:0x940
	ds_read_b64_tr_b16 v[98:99], v136 offset:0xdc0
	s_waitcnt lgkmcnt(8)
	s_setprio 1
	v_mfma_f32_32x32x16_bf16 v[48:63], v[48:51], v[84:87], 0
	v_mfma_f32_32x32x16_bf16 v[48:63], v[68:71], v[80:83], v[48:63]
	v_mfma_f32_32x32x16_bf16 v[48:63], v[72:75], v[10:13], v[48:63]
	v_mfma_f32_32x32x16_bf16 v[48:63], v[76:79], v[6:9], v[48:63]
	s_setprio 0
	v_mfma_f32_32x32x16_bf16 v[64:79], v[64:67], v[84:87], 0
	ds_read_b64_tr_b16 v[124:125], v136 offset:0x1200
	ds_read_b64_tr_b16 v[126:127], v136 offset:0x1680
	ds_read_b64_tr_b16 v[120:121], v136 offset:0x1240
	ds_read_b64_tr_b16 v[122:123], v136 offset:0x16c0
	s_cmp_le_i32 s51, s48
	v_mfma_f32_32x32x16_bf16 v[64:79], v[104:107], v[80:83], v[64:79]
	v_mfma_f32_32x32x16_bf16 v[64:79], v[108:111], v[10:13], v[64:79]
	ds_read_b64_tr_b16 v[108:109], v136 offset:0x1b00
	ds_read_b64_tr_b16 v[110:111], v136 offset:0x1f80
	ds_read_b64_tr_b16 v[104:105], v136 offset:0x1b40
	ds_read_b64_tr_b16 v[106:107], v136 offset:0x1fc0
	v_mfma_f32_32x32x16_bf16 v[64:79], v[132:135], v[6:9], v[64:79]
	s_cbranch_scc1 .LBB0_1314
	v_add_u32_e32 v132, s51, v128
	v_subrev_u32_e32 v133, 63, v132
	v_cmp_le_i32_e32 vcc, v133, v15
	s_nop 7
	v_cndmask_b32_e32 v64, v204, v64, vcc
	v_cmp_lt_i32_e32 vcc, v133, v15
	v_subrev_u32_e32 v133, 61, v132
	s_nop 0
	v_cndmask_b32_e32 v65, v204, v65, vcc
	v_cmp_le_i32_e32 vcc, v133, v15
	v_subrev_u32_e32 v133, 60, v132
	s_nop 0
	v_cndmask_b32_e32 v66, v204, v66, vcc
	v_cmp_le_i32_e32 vcc, v133, v15
	v_subrev_u32_e32 v133, 55, v132
	s_nop 0
	v_cndmask_b32_e32 v67, v204, v67, vcc
	v_cmp_le_i32_e32 vcc, v133, v15
	v_subrev_u32_e32 v133, 54, v132
	s_nop 0
	v_cndmask_b32_e32 v68, v204, v68, vcc
	v_cmp_le_i32_e32 vcc, v133, v15
	v_subrev_u32_e32 v133, 53, v132
	s_nop 0
	v_cndmask_b32_e32 v69, v204, v69, vcc
	v_cmp_le_i32_e32 vcc, v133, v15
	v_subrev_u32_e32 v133, 52, v132
	s_nop 0
	v_cndmask_b32_e32 v70, v204, v70, vcc
	v_cmp_le_i32_e32 vcc, v133, v15
	v_subrev_u32_e32 v133, 47, v132
	s_nop 0
	v_cndmask_b32_e32 v71, v204, v71, vcc
	v_cmp_le_i32_e32 vcc, v133, v15
	v_subrev_u32_e32 v133, 46, v132
	s_nop 0
	v_cndmask_b32_e32 v72, v204, v72, vcc
	v_cmp_le_i32_e32 vcc, v133, v15
	v_subrev_u32_e32 v133, 45, v132
	s_nop 0
	v_cndmask_b32_e32 v73, v204, v73, vcc
	v_cmp_le_i32_e32 vcc, v133, v15
	v_subrev_u32_e32 v133, 44, v132
	s_nop 0
	v_cndmask_b32_e32 v74, v204, v74, vcc
	v_cmp_le_i32_e32 vcc, v133, v15
	v_subrev_u32_e32 v133, 39, v132
	s_nop 0
	v_cndmask_b32_e32 v75, v204, v75, vcc
	v_cmp_le_i32_e32 vcc, v133, v15
	v_subrev_u32_e32 v133, 38, v132
	s_nop 0
	v_cndmask_b32_e32 v76, v204, v76, vcc
	v_cmp_le_i32_e32 vcc, v133, v15
	v_subrev_u32_e32 v133, 37, v132
	s_nop 0
	v_cndmask_b32_e32 v77, v204, v77, vcc
	v_cmp_le_i32_e32 vcc, v133, v15
	v_subrev_u32_e32 v133, 36, v132
	s_nop 0
	v_cndmask_b32_e32 v78, v204, v78, vcc
	v_cmp_le_i32_e32 vcc, v133, v15
	v_subrev_u32_e32 v133, 31, v132
	s_nop 0
	v_cndmask_b32_e32 v79, v204, v79, vcc
	v_cmp_le_i32_e32 vcc, v133, v15
	v_subrev_u32_e32 v133, 30, v132
	s_nop 0
	v_cndmask_b32_e32 v48, v204, v48, vcc
	v_cmp_le_i32_e32 vcc, v133, v15
	v_subrev_u32_e32 v133, 29, v132
	s_nop 0
	v_cndmask_b32_e32 v49, v204, v49, vcc
	v_cmp_le_i32_e32 vcc, v133, v15
	v_subrev_u32_e32 v133, 28, v132
	s_nop 0
	v_cndmask_b32_e32 v50, v204, v50, vcc
	v_cmp_le_i32_e32 vcc, v133, v15
	v_subrev_u32_e32 v133, 23, v132
	s_nop 0
	v_cndmask_b32_e32 v51, v204, v51, vcc
	v_cmp_le_i32_e32 vcc, v133, v15
	v_subrev_u32_e32 v133, 22, v132
	s_nop 0
	v_cndmask_b32_e32 v52, v204, v52, vcc
	v_cmp_le_i32_e32 vcc, v133, v15
	v_subrev_u32_e32 v133, 21, v132
	s_nop 0
	v_cndmask_b32_e32 v53, v204, v53, vcc
	v_cmp_le_i32_e32 vcc, v133, v15
	v_subrev_u32_e32 v133, 20, v132
	s_nop 0
	v_cndmask_b32_e32 v54, v204, v54, vcc
	v_cmp_le_i32_e32 vcc, v133, v15
	v_add_u32_e32 v133, -15, v132
	s_nop 0
	v_cndmask_b32_e32 v55, v204, v55, vcc
	v_cmp_le_i32_e32 vcc, v133, v15
	v_add_u32_e32 v133, -14, v132
	s_nop 0
	v_cndmask_b32_e32 v56, v204, v56, vcc
	v_cmp_le_i32_e32 vcc, v133, v15
	v_add_u32_e32 v133, -13, v132
	s_nop 0
	v_cndmask_b32_e32 v57, v204, v57, vcc
	v_cmp_le_i32_e32 vcc, v133, v15
	v_add_u32_e32 v133, -12, v132
	s_nop 0
	v_cndmask_b32_e32 v58, v204, v58, vcc
	v_cmp_le_i32_e32 vcc, v133, v15
	v_add_u32_e32 v133, -7, v132
	s_nop 0
	v_cndmask_b32_e32 v59, v204, v59, vcc
	v_cmp_le_i32_e32 vcc, v133, v15
	v_add_u32_e32 v133, -6, v132
	s_nop 0
	v_cndmask_b32_e32 v60, v204, v60, vcc
	v_cmp_le_i32_e32 vcc, v133, v15
	v_add_u32_e32 v133, -5, v132
	v_add_u32_e32 v132, -4, v132
	v_cndmask_b32_e32 v61, v204, v61, vcc
	v_cmp_le_i32_e32 vcc, v133, v15
	s_nop 1
	v_cndmask_b32_e32 v62, v204, v62, vcc
	v_cmp_le_i32_e32 vcc, v132, v15
	s_nop 1
	v_cndmask_b32_e32 v63, v204, v63, vcc

; #define FL_LSTORE(buf) do { *(LAS u32x4*)(lds + AT_K + (buf) * KBUF + srow * KP2 + sch * 16) = rk1; \
;         if (DQK == 96 && tid < 256) *(LAS u32x4*)(lds + AT_K + (buf) * KBUF + srow2 * KP2 + 128 + sch2 * 16) = rk2; \
;         *(LAS u32x4*)(lds + AT_V + (buf) * VBUF + srow * VP2 + sch * 16) = rv; } while (0)
; template <int DQK, int MODE> ...
;     ...
;         if (t + 1 < t1) { FL_LSTORE(cur ^ 1); if (t + 2 < t1) FL_GLOAD(t + 2); }
;         __syncthreads();
.LBB0_1319:
	s_bitcmp1_b32 s50, 0
	s_cbranch_scc0 .Lsel_even
	s_add_i32 s4, s50, 3
	s_cmp_ge_u32 s4, s47
	s_cbranch_scc1 .Lselq_latch
	s_and_b32 s4, s4, 7
	s_cmp_gt_u32 s4, 5
	s_cselect_b32 s5, 0xc00, 0
	s_add_i32 s5, s5, 0x12000
	s_mulk_i32 s4, 0x2400
	v_add_u32_e32 v229, s4, v129
	s_add_i32 s4, s4, s5
	v_add_u32_e32 v230, s4, v129
	s_add_i32 s4, s50, 4
	s_and_b32 s4, s4, 7
	s_cmp_gt_u32 s4, 5
	s_cselect_b32 s5, 0xc00, 0
	s_add_i32 s5, s5, 0x12000
	s_mulk_i32 s4, 0x2400
	v_add_u32_e32 v228, s4, v129
	s_add_i32 s4, s4, s5
	v_add_u32_e32 v231, s4, v129
	s_waitcnt vmcnt(0)
	ds_write_b128 v229, v[92:95]
	ds_write_b128 v230, v[88:91]
	ds_write_b128 v228, v[218:221]
	ds_write_b128 v231, v[222:225]
	s_add_i32 s4, s50, 5
	s_cmp_ge_u32 s4, s47
	s_cbranch_scc1 .Lselq_latch
	v_lshl_add_u64 v[230:231], s[28:29], 0, v[0:1]
	global_load_dwordx4 v[92:95], v[230:231], off offset:2112
	global_load_dwordx4 v[88:91], v[230:231], off offset:2368
	v_add_u32_e32 v228, 0x50000, v0
	v_mov_b32_e32 v229, v1
	v_lshl_add_u64 v[228:229], s[28:29], 0, v[228:229]
	global_load_dwordx4 v[218:221], v[228:229], off offset:2112
	global_load_dwordx4 v[222:225], v[228:229], off offset:2368
.Lselq_latch:
	s_and_b32 s4, s50, 3
	s_cmp_eq_u32 s4, 3
	s_cbranch_scc1 .LBB0_1310

; template <int DQK, int MODE> ...
;     ...
;         if (active) {
;             f32x16 s[2];
;             bf16x8 ka[2][NKS]; s16x4 vlo[2][2][2], vhi[2][2][2];
;             {
;                 const unsigned kaddr = (unsigned)(unsigned long)(lds + AT_K + cur * KBUF) + (unsigned)(r32 * KP2 + hi * 16);
;                 const unsigned vaddr = (unsigned)(unsigned long)(lds + AT_V + cur * VBUF) + (unsigned)((4 * hi + ((lane & 15) >> 2)) * VP2 + 32 * ((lane >> 4) & 1) + 8 * (lane & 3));
; #pragma unroll
;                 for (int kb = 0; kb < 2; ++kb)
; #pragma unroll
;                     for (int ks = 0; ks < NKS; ++ks) asm volatile("ds_read_b128 %0, %1 offset:%2" : "=v"(ka[kb][ks]) : "v"(kaddr), "n"(kb * 32 * KP2 + ks * 32) : "memory");
; #pragma unroll
;                 for (int s2 = 0; s2 < 2; ++s2)
; #pragma unroll
;                     for (int d0 = 0; d0 < 2; ++d0) {
;                         asm volatile("ds_read_b64_tr_b16 %0, %1 offset:%2" : "=v"(vlo[0][s2][d0]) : "v"(vaddr), "n"(16 * s2 * VP2 + 64 * d0) : "memory");
;                         asm volatile("ds_read_b64_tr_b16 %0, %1 offset:%2" : "=v"(vhi[0][s2][d0]) : "v"(vaddr), "n"(16 * s2 * VP2 + 64 * d0 + 8 * VP2) : "memory");
;                     }
;                 asm volatile("s_waitcnt lgkmcnt(8)" ::: "memory");
; #pragma unroll
;                 for (int kb = 0; kb < 2; ++kb)
; #pragma unroll
;                     for (int ks = 0; ks < NKS; ++ks) asm volatile("" : "+v"(ka[kb][ks]));
;                 s[0] = (f32x16){}; s[1] = (f32x16){};
;                 __builtin_amdgcn_s_setprio(1);
; #pragma unroll
;                 for (int ks = 0; ks < NKS; ++ks) { s[0] = MFMA32(ka[0][ks], qf[ks], s[0]); s[1] = MFMA32(ka[1][ks], qf[ks], s[1]); }
;                 __builtin_amdgcn_s_setprio(0);
; #pragma unroll
;                 for (int s2 = 0; s2 < 2; ++s2)
; #pragma unroll
;                     for (int d0 = 0; d0 < 2; ++d0) {
;                         asm volatile("ds_read_b64_tr_b16 %0, %1 offset:%2" : "=v"(vlo[1][s2][d0]) : "v"(vaddr), "n"((32 + 16 * s2) * VP2 + 64 * d0) : "memory");
;                         asm volatile("ds_read_b64_tr_b16 %0, %1 offset:%2" : "=v"(vhi[1][s2][d0]) : "v"(vaddr), "n"((32 + 16 * s2) * VP2 + 64 * d0 + 8 * VP2) : "memory");
;                     }
;             }
;             bool need_mask;
;             if (MODE == MODE_CMP) need_mask = true;
.LBB0_1321:
	s_lshl_b32 s4, s0, 6
	s_cmp_gt_i32 s4, s49
	s_cbranch_scc1 .LBB0_1329
	s_and_b32 s5, s0, 7
	s_mulk_i32 s5, 0x2400
	s_add_i32 s1, s1, s5
	v_add_u32_e32 v0, s1, v131
	ds_read_b128 v[64:67], v0 offset:0
	ds_read_b128 v[104:107], v0 offset:32
	ds_read_b128 v[108:111], v0 offset:64
	ds_read_b128 v[112:115], v0 offset:0x60
	ds_read_b128 v[48:51], v0 offset:0x1200
	ds_read_b128 v[68:71], v0 offset:0x1220
	ds_read_b128 v[72:75], v0 offset:0x1240
	s_and_b32 s5, s0, 7
	s_cmp_gt_u32 s5, 5
	s_cselect_b32 s5, 0xc00, 0
	s_add_i32 s5, s5, 0x12000
	s_add_i32 s1, s1, s5
	ds_read_b128 v[76:79], v0 offset:0x1260
	v_add_u32_e32 v0, s1, v130
	ds_read_b64_tr_b16 v[100:101], v0 offset:0
	ds_read_b64_tr_b16 v[102:103], v0 offset:0x480
	ds_read_b64_tr_b16 v[96:97], v0 offset:64
	ds_read_b64_tr_b16 v[98:99], v0 offset:0x4c0
	s_waitcnt vmcnt(0)
	ds_read_b64_tr_b16 v[92:93], v0 offset:0x900
	ds_read_b64_tr_b16 v[94:95], v0 offset:0xd80
	ds_read_b64_tr_b16 v[88:89], v0 offset:0x940
	ds_read_b64_tr_b16 v[90:91], v0 offset:0xdc0
	s_waitcnt lgkmcnt(8)
	s_setprio 1
	v_mfma_f32_32x32x16_bf16 v[48:63], v[48:51], v[84:87], 0
	v_mfma_f32_32x32x16_bf16 v[48:63], v[68:71], v[80:83], v[48:63]
	v_mfma_f32_32x32x16_bf16 v[48:63], v[72:75], v[10:13], v[48:63]
	v_mfma_f32_32x32x16_bf16 v[48:63], v[76:79], v[6:9], v[48:63]
	s_setprio 0
	v_mfma_f32_32x32x16_bf16 v[64:79], v[64:67], v[84:87], 0
	s_or_b32 s1, s4, 63
	s_cmp_le_i32 s1, s48
	v_mfma_f32_32x32x16_bf16 v[64:79], v[104:107], v[80:83], v[64:79]
	ds_read_b64_tr_b16 v[104:105], v0 offset:0x1200
	ds_read_b64_tr_b16 v[106:107], v0 offset:0x1680
	ds_read_b64_tr_b16 v[84:85], v0 offset:0x1240
	ds_read_b64_tr_b16 v[86:87], v0 offset:0x16c0
	ds_read_b64_tr_b16 v[80:81], v0 offset:0x1b00
	ds_read_b64_tr_b16 v[82:83], v0 offset:0x1f80
	v_mfma_f32_32x32x16_bf16 v[64:79], v[108:111], v[10:13], v[64:79]
	ds_read_b64_tr_b16 v[10:11], v0 offset:0x1b40
	ds_read_b64_tr_b16 v[12:13], v0 offset:0x1fc0
	v_mfma_f32_32x32x16_bf16 v[64:79], v[112:115], v[6:9], v[64:79]
	s_cbranch_scc1 .LBB0_1324
	v_or_b32_e32 v0, s4, v128
	v_cmp_le_i32_e32 vcc, v0, v15
	v_or_b32_e32 v6, 2, v0
	s_nop 7
	v_cndmask_b32_e32 v64, v204, v64, vcc
	v_cmp_lt_i32_e32 vcc, v0, v15
	s_nop 1
	v_cndmask_b32_e32 v65, v204, v65, vcc
	v_cmp_le_i32_e32 vcc, v6, v15
	v_or_b32_e32 v6, 3, v0
	s_nop 0
	v_cndmask_b32_e32 v66, v204, v66, vcc
	v_cmp_le_i32_e32 vcc, v6, v15
	v_or_b32_e32 v6, 8, v0
	s_nop 0
	v_cndmask_b32_e32 v67, v204, v67, vcc
	v_cmp_le_i32_e32 vcc, v6, v15
	v_or_b32_e32 v6, 9, v0
	s_nop 0
	v_cndmask_b32_e32 v68, v204, v68, vcc
	v_cmp_le_i32_e32 vcc, v6, v15
	v_or_b32_e32 v6, 10, v0
	s_nop 0
	v_cndmask_b32_e32 v69, v204, v69, vcc
	v_cmp_le_i32_e32 vcc, v6, v15
	v_or_b32_e32 v6, 11, v0
	s_nop 0
	v_cndmask_b32_e32 v70, v204, v70, vcc
	v_cmp_le_i32_e32 vcc, v6, v15
	v_or_b32_e32 v6, 16, v0
	s_nop 0
	v_cndmask_b32_e32 v71, v204, v71, vcc
	v_cmp_le_i32_e32 vcc, v6, v15
	v_or_b32_e32 v6, 17, v0
	s_nop 0
	v_cndmask_b32_e32 v72, v204, v72, vcc
	v_cmp_le_i32_e32 vcc, v6, v15
	v_or_b32_e32 v6, 18, v0
	s_nop 0
	v_cndmask_b32_e32 v73, v204, v73, vcc
	v_cmp_le_i32_e32 vcc, v6, v15
	v_or_b32_e32 v6, 19, v0
	s_nop 0
	v_cndmask_b32_e32 v74, v204, v74, vcc
	v_cmp_le_i32_e32 vcc, v6, v15
	v_or_b32_e32 v6, 24, v0
	s_nop 0
	v_cndmask_b32_e32 v75, v204, v75, vcc
	v_cmp_le_i32_e32 vcc, v6, v15
	v_or_b32_e32 v6, 25, v0
	s_nop 0
	v_cndmask_b32_e32 v76, v204, v76, vcc
	v_cmp_le_i32_e32 vcc, v6, v15
	v_or_b32_e32 v6, 26, v0
	s_nop 0
	v_cndmask_b32_e32 v77, v204, v77, vcc
	v_cmp_le_i32_e32 vcc, v6, v15
	v_or_b32_e32 v6, 27, v0
	s_nop 0
	v_cndmask_b32_e32 v78, v204, v78, vcc
	v_cmp_le_i32_e32 vcc, v6, v15
	v_or_b32_e32 v6, 32, v0
	s_nop 0
	v_cndmask_b32_e32 v79, v204, v79, vcc
	v_cmp_le_i32_e32 vcc, v6, v15
	v_or_b32_e32 v6, 33, v0
	s_nop 0
	v_cndmask_b32_e32 v48, v204, v48, vcc
	v_cmp_le_i32_e32 vcc, v6, v15
	v_or_b32_e32 v6, 34, v0
	s_nop 0
	v_cndmask_b32_e32 v49, v204, v49, vcc
	v_cmp_le_i32_e32 vcc, v6, v15
	v_or_b32_e32 v6, 35, v0
	s_nop 0
	v_cndmask_b32_e32 v50, v204, v50, vcc
	v_cmp_le_i32_e32 vcc, v6, v15
	v_or_b32_e32 v6, 40, v0
	s_nop 0
	v_cndmask_b32_e32 v51, v204, v51, vcc
	v_cmp_le_i32_e32 vcc, v6, v15
	v_or_b32_e32 v6, 41, v0
	s_nop 0
	v_cndmask_b32_e32 v52, v204, v52, vcc
	v_cmp_le_i32_e32 vcc, v6, v15
	v_or_b32_e32 v6, 42, v0
	s_nop 0
	v_cndmask_b32_e32 v53, v204, v53, vcc
	v_cmp_le_i32_e32 vcc, v6, v15
	v_or_b32_e32 v6, 43, v0
	s_nop 0
	v_cndmask_b32_e32 v54, v204, v54, vcc
	v_cmp_le_i32_e32 vcc, v6, v15
	v_or_b32_e32 v6, 48, v0
	s_nop 0
	v_cndmask_b32_e32 v55, v204, v55, vcc
	v_cmp_le_i32_e32 vcc, v6, v15
	v_or_b32_e32 v6, 49, v0
	s_nop 0
	v_cndmask_b32_e32 v56, v204, v56, vcc
	v_cmp_le_i32_e32 vcc, v6, v15
	v_or_b32_e32 v6, 50, v0
	s_nop 0
	v_cndmask_b32_e32 v57, v204, v57, vcc
	v_cmp_le_i32_e32 vcc, v6, v15
	v_or_b32_e32 v6, 51, v0
	s_nop 0
	v_cndmask_b32_e32 v58, v204, v58, vcc
	v_cmp_le_i32_e32 vcc, v6, v15
	v_or_b32_e32 v6, 56, v0
	s_nop 0
	v_cndmask_b32_e32 v59, v204, v59, vcc
	v_cmp_le_i32_e32 vcc, v6, v15
	v_or_b32_e32 v6, 57, v0
	s_nop 0
	v_cndmask_b32_e32 v60, v204, v60, vcc
	v_cmp_le_i32_e32 vcc, v6, v15
	v_or_b32_e32 v6, 58, v0
	v_or_b32_e32 v0, 59, v0
	v_cndmask_b32_e32 v61, v204, v61, vcc
	v_cmp_le_i32_e32 vcc, v6, v15
	s_nop 1
	v_cndmask_b32_e32 v62, v204, v62, vcc
	v_cmp_le_i32_e32 vcc, v0, v15
	s_nop 1
	v_cndmask_b32_e32 v63, v204, v63, vcc

; __global__ void __launch_bounds__(512) mega_fwd(Params P) {
;     extern __shared__ __attribute__((aligned(16))) unsigned char lds_raw[];
	.amdhsa_kernel _Z8mega_fwd6Params
		.amdhsa_group_segment_fixed_size 31744
		.amdhsa_private_segment_fixed_size 0
		.amdhsa_kernarg_size 464
		.amdhsa_user_sgpr_count 2
		.amdhsa_user_sgpr_dispatch_ptr 0
		.amdhsa_user_sgpr_queue_ptr 0
		.amdhsa_user_sgpr_kernarg_segment_ptr 1
		.amdhsa_user_sgpr_dispatch_id 0
		.amdhsa_user_sgpr_kernarg_preload_length 0
		.amdhsa_user_sgpr_kernarg_preload_offset 0
		.amdhsa_user_sgpr_private_segment_size 0
		.amdhsa_uses_dynamic_stack 0
		.amdhsa_enable_private_segment 0
		.amdhsa_system_sgpr_workgroup_id_x 1
		.amdhsa_system_sgpr_workgroup_id_y 0
		.amdhsa_system_sgpr_workgroup_id_z 0
		.amdhsa_system_sgpr_workgroup_info 0
		.amdhsa_system_vgpr_workitem_id 2
		.amdhsa_next_free_vgpr 256
		.amdhsa_next_free_sgpr 102
		.amdhsa_accum_offset 256
		.amdhsa_reserve_vcc 1
		.amdhsa_float_round_mode_32 0
		.amdhsa_float_round_mode_16_64 0
		.amdhsa_float_denorm_mode_32 3
		.amdhsa_float_denorm_mode_16_64 3
		.amdhsa_dx10_clamp 1
		.amdhsa_ieee_mode 1
		.amdhsa_fp16_overflow 0
		.amdhsa_tg_split 0
		.amdhsa_exception_fp_ieee_invalid_op 0
		.amdhsa_exception_fp_denorm_src 0
		.amdhsa_exception_fp_ieee_div_zero 0
		.amdhsa_exception_fp_ieee_overflow 0
		.amdhsa_exception_fp_ieee_underflow 0
		.amdhsa_exception_fp_ieee_inexact 0
		.amdhsa_exception_int_div_zero 0
	.end_amdhsa_kernel

; __global__ void __launch_bounds__(512) mega_fwd(Params P) {
;     extern __shared__ __attribute__((aligned(16))) unsigned char lds_raw[];
amdhsa.kernels:
  - .agpr_count:     0
    .args:
      - .offset:         0
        .size:           208
        .value_kind:     by_value
      - .offset:         208
        .size:           4
        .value_kind:     hidden_block_count_x
      - .offset:         212
        .size:           4
        .value_kind:     hidden_block_count_y
      - .offset:         216
        .size:           4
        .value_kind:     hidden_block_count_z
      - .offset:         220
        .size:           2
        .value_kind:     hidden_group_size_x
      - .offset:         222
        .size:           2
        .value_kind:     hidden_group_size_y
      - .offset:         224
        .size:           2
        .value_kind:     hidden_group_size_z
      - .offset:         226
        .size:           2
        .value_kind:     hidden_remainder_x
      - .offset:         228
        .size:           2
        .value_kind:     hidden_remainder_y
      - .offset:         230
        .size:           2
        .value_kind:     hidden_remainder_z
      - .offset:         248
        .size:           8
        .value_kind:     hidden_global_offset_x
      - .offset:         256
        .size:           8
        .value_kind:     hidden_global_offset_y
      - .offset:         264
        .size:           8
        .value_kind:     hidden_global_offset_z
      - .offset:         272
        .size:           2
        .value_kind:     hidden_grid_dims
      - .offset:         296
        .size:           8
        .value_kind:     hidden_multigrid_sync_arg
      - .offset:         328
        .size:           4
        .value_kind:     hidden_dynamic_lds_size
    .group_segment_fixed_size: 31744
    .kernarg_segment_align: 8
    .kernarg_segment_size: 464
    .language:       OpenCL C
    .language_version:
      - 2
      - 0
    .max_flat_workgroup_size: 512
    .name:           _Z8mega_fwd6Params
    .private_segment_fixed_size: 0
    .sgpr_count:     108
    .sgpr_spill_count: 96
    .symbol:         _Z8mega_fwd6Params.kd
    .uniform_work_group_size: 1
    .uses_dynamic_stack: false
    .vgpr_count:     256
    .vgpr_spill_count: 0
    .wavefront_size: 64
